# stacked on best: mLSTM gate prefix sum / prefix max done with DPP row scans instead of 12 dependent ds_bpermute round trips; KTs LDS swizzle; XCD barrier after setup
# speedup vs baseline: 1.0059x; 1.0059x over previous
; DI void mlstm_item(int j, int item, LAS unsigned char* lds) {
;     ...
;         if (wave == 0) {
;             const float a0 = lfs[2 * lane], a1 = lfs[2 * lane + 1]; const float c1 = a0 + a1;
;             float x = c1;
; #pragma unroll
;             for (int o = 1; o < 64; o <<= 1) { const float y = __shfl_up(x, o); if (lane >= o) x += y; }
;             const float ex = x - c1; const float bc0 = ex + a0, bc1 = ex + c1;
;             const float g0 = ics[2 * lane] - bc0, g1 = ics[2 * lane + 1] - bc1;
;             float pm = fmaxf(g0, g1);
; #pragma unroll
;             for (int o = 1; o < 64; o <<= 1) { const float y = __shfl_up(pm, o); if (lane >= o) pm = fmaxf(pm, y); }
;             float pe = __shfl_up(pm, 1); if (lane == 0) pe = -3.0e38f;
;             const float pm0 = fmaxf(pe, g0), pm1 = fmaxf(pe, fmaxf(g0, g1));
;             const float bl = __shfl(x, 63), gmax = __shfl(pm, 63);
;             const float mnew = fmaxf(bl + mst, bl + gmax);
;             bcs[2 * lane] = bc0; bcs[2 * lane + 1] = bc1; gs[2 * lane] = g0; gs[2 * lane + 1] = g1;
;             ats[2 * lane] = fmaxf(pm0, mst); ats[2 * lane + 1] = fmaxf(pm1, mst);
;             wss[2 * lane] = __expf(bl + g0 - mnew) * scale; wss[2 * lane + 1] = __expf(bl + g1 - mnew) * scale;
;             if (lane == 0) { scal[0] = mnew; scal[1] = __expf(bl + mst - mnew); }
.LBB0_527:
	s_or_b64 exec, exec, s[36:37]
	s_andn2_b64 vcc, exec, s[26:27]
	s_waitcnt lgkmcnt(0)
	s_barrier
	s_cbranch_vccnz .LBB0_531
	ds_read_b64 v[52:53], v111
	s_mov_b32 s2, 0x3db504f3
	s_waitcnt lgkmcnt(0)
	v_pk_add_f32 v[54:55], v[52:53], v[52:53] op_sel:[0,1] op_sel_hi:[1,0]
	v_mov_b32_e32 v53, v54
	v_mov_b32_e32 v50, v54
	s_nop 1
	v_add_f32_dpp v50, v50, v50 row_shr:1 row_mask:0xf bank_mask:0xf
	s_nop 1
	v_add_f32_dpp v50, v50, v50 row_shr:2 row_mask:0xf bank_mask:0xf
	s_nop 1
	v_add_f32_dpp v50, v50, v50 row_shr:4 row_mask:0xf bank_mask:0xf
	s_nop 1
	v_add_f32_dpp v50, v50, v50 row_shr:8 row_mask:0xf bank_mask:0xf
	s_nop 1
	v_add_f32_dpp v50, v50, v50 row_bcast:15 row_mask:0xa bank_mask:0xf
	s_nop 1
	v_add_f32_dpp v50, v50, v50 row_bcast:31 row_mask:0xc bank_mask:0xf
	ds_bpermute_b32 v57, v126, v50
	v_sub_f32_e32 v56, v50, v54
	ds_read_b64 v[54:55], v112
	s_waitcnt lgkmcnt(1)
	v_pk_add_f32 v[52:53], v[52:53], v[56:57] op_sel_hi:[1,0]
	v_add_f32_e32 v50, v145, v57
	s_waitcnt lgkmcnt(0)
	v_pk_add_f32 v[54:55], v[54:55], v[52:53] neg_lo:[0,1] neg_hi:[0,1]
	ds_write_b64 v113, v[52:53]
	ds_write_b64 v114, v[54:55]
	v_max_f32_e32 v56, v54, v55
	v_mov_b32_e32 v51, v56
	s_nop 1
	v_max_f32_dpp v51, v51, v51 row_shr:1 row_mask:0xf bank_mask:0xf
	s_nop 1
	v_max_f32_dpp v51, v51, v51 row_shr:2 row_mask:0xf bank_mask:0xf
	s_nop 1
	v_max_f32_dpp v51, v51, v51 row_shr:4 row_mask:0xf bank_mask:0xf
	s_nop 1
	v_max_f32_dpp v51, v51, v51 row_shr:8 row_mask:0xf bank_mask:0xf
	s_nop 1
	v_max_f32_dpp v51, v51, v51 row_bcast:15 row_mask:0xa bank_mask:0xf
	s_nop 1
	v_max_f32_dpp v51, v51, v51 row_bcast:31 row_mask:0xc bank_mask:0xf
	ds_bpermute_b32 v58, v120, v51
	ds_bpermute_b32 v51, v126, v51
	s_waitcnt lgkmcnt(1)
	v_cndmask_b32_e64 v58, v58, v235, s[44:45]
	s_waitcnt lgkmcnt(0)
	v_add_f32_e32 v51, v57, v51
	v_max3_f32 v52, v58, v54, v145
	v_max3_f32 v53, v58, v56, v145
	v_max_f32_e32 v51, v50, v51
	ds_write_b64 v115, v[52:53]
	v_add_f32_e32 v52, v54, v57
	v_add_f32_e32 v53, v55, v57
	v_sub_f32_e32 v52, v52, v51
	v_sub_f32_e32 v53, v53, v51
	v_mul_f32_e32 v52, 0x3fb8aa3b, v52
	v_mul_f32_e32 v53, 0x3fb8aa3b, v53
	v_exp_f32_e32 v52, v52
	v_exp_f32_e32 v53, v53
	s_nop 0
	v_pk_mul_f32 v[52:53], v[52:53], s[2:3] op_sel_hi:[1,0]
	ds_write_b64 v116, v[52:53]
	s_and_saveexec_b64 s[2:3], s[44:45]
	s_cbranch_execz .LBB0_530
	v_sub_f32_e32 v50, v50, v51
	v_mul_f32_e32 v50, 0x3fb8aa3b, v50
	v_exp_f32_e32 v50, v50
	ds_write_b32 v184, v51
	ds_write_b32 v185, v50
